# v-pass of PEER rewritten by hand: rolling prefetch, lane-group reduce-scatter via permlane swaps and DPP instead of ds_bpermute
# speedup vs baseline: 1.0070x; 1.0070x over previous
; __global__ void __launch_bounds__(NTHR, 2) fwd_megakernel(Args a) {
;     ...
;             float ssk = 0.f;
; #pragma unroll 1
;             for (int vs = 0; vs < 16; ++vs) {
;                 const unsigned char* Vs = V8 + (size_t)vs * (16384 * 128) + sub * 16;
; #pragma unroll 1
;                 for (int k = 0; k < kn; ++k) {
;                     const size_t t = (size_t)gw + (size_t)(k0 + k) * NGW;
;                     u32x4 r[16]; float wi[16];
; #pragma unroll
;                     for (int i = 0; i < 16; ++i) { const unsigned e = (unsigned)EL[k * 128 + 8 * i + grp]; r[i] = *(const u32x4*)(Vs + e * 128u); wi[i] = HW[k * 128 + 8 * i + grp]; }
;                     float* hp = H + t * D + vs * 128 + 2 * sp;
;                     f32x2 hv = __builtin_nontemporal_load((const f32x2*)hp);
;                     const f32x2 gn = *(const f32x2*)(a.ple_norm + vs * 128 + 2 * sp);
.LBB0_912:
	v_mov_b32_e32 v134, 0
	s_and_b64 vcc, exec, s[28:29]
	s_cbranch_vccnz .LBB0_917
	v_and_b32_e32 v184, 7, v64
	s_add_u32 s98, s50, 0x6000000
	s_addc_u32 s99, s51, 0
	v_lshlrev_b32_e32 v184, 4, v184
	s_mov_b64 s[30:31], 0x200
	s_lshl_b32 s100, s33, 4
	s_mov_b32 s0, 0
	s_mov_b32 s101, 0
	s_mov_b32 s1, 0
	v_add_u32_e32 v186, 0x2000, v124
	v_mov_b32_e32 v185, v124
	ds_read2_b32 v[166:167], v124 offset1:8
	ds_read2_b32 v[168:169], v124 offset0:16 offset1:24
	ds_read2_b32 v[170:171], v124 offset0:32 offset1:40
	ds_read2_b32 v[172:173], v124 offset0:48 offset1:56
	ds_read2_b32 v[174:175], v124 offset0:64 offset1:72
	ds_read2_b32 v[176:177], v124 offset0:80 offset1:88
	ds_read2_b32 v[178:179], v124 offset0:96 offset1:104
	ds_read2_b32 v[180:181], v124 offset0:112 offset1:120
	ds_read2_b32 v[150:151], v186 offset1:8
	ds_read2_b32 v[152:153], v186 offset0:16 offset1:24
	ds_read2_b32 v[154:155], v186 offset0:32 offset1:40
	ds_read2_b32 v[156:157], v186 offset0:48 offset1:56
	ds_read2_b32 v[158:159], v186 offset0:64 offset1:72
	ds_read2_b32 v[160:161], v186 offset0:80 offset1:88
	ds_read2_b32 v[162:163], v186 offset0:96 offset1:104
	ds_read2_b32 v[164:165], v186 offset0:112 offset1:120
	v_mov_b64_e32 v[196:197], v[90:91]
	v_mov_b64_e32 v[192:193], v[90:91]
	v_mov_b64_e32 v[188:189], v[90:91]
	v_mov_b64_e32 v[198:199], v[88:89]
	v_mov_b64_e32 v[194:195], v[88:89]
	v_mov_b64_e32 v[190:191], v[88:89]
	v_mov_b64_e32 v[200:201], v[74:75]
	s_waitcnt lgkmcnt(0)
	v_lshl_add_u32 v182, v166, 7, v184
	global_load_dwordx4 v[0:3], v182, s[98:99]
	v_lshl_add_u32 v183, v167, 7, v184
	global_load_dwordx4 v[4:7], v183, s[98:99]
	v_lshl_add_u32 v182, v168, 7, v184
	global_load_dwordx4 v[8:11], v182, s[98:99]
	v_lshl_add_u32 v183, v169, 7, v184
	global_load_dwordx4 v[12:15], v183, s[98:99]
	v_lshl_add_u32 v182, v170, 7, v184
	global_load_dwordx4 v[16:19], v182, s[98:99]
	v_lshl_add_u32 v183, v171, 7, v184
	global_load_dwordx4 v[20:23], v183, s[98:99]
	v_lshl_add_u32 v182, v172, 7, v184
	global_load_dwordx4 v[24:27], v182, s[98:99]
	v_lshl_add_u32 v183, v173, 7, v184
	global_load_dwordx4 v[28:31], v183, s[98:99]
	v_lshl_add_u32 v182, v174, 7, v184
	global_load_dwordx4 v[32:35], v182, s[98:99]
	v_lshl_add_u32 v183, v175, 7, v184
	global_load_dwordx4 v[36:39], v183, s[98:99]
	v_lshl_add_u32 v182, v176, 7, v184
	global_load_dwordx4 v[40:43], v182, s[98:99]
	v_lshl_add_u32 v183, v177, 7, v184
	global_load_dwordx4 v[44:47], v183, s[98:99]
	v_lshl_add_u32 v182, v178, 7, v184
	global_load_dwordx4 v[48:51], v182, s[98:99]
	v_lshl_add_u32 v183, v179, 7, v184
	global_load_dwordx4 v[52:55], v183, s[98:99]
	v_lshl_add_u32 v182, v180, 7, v184
	global_load_dwordx4 v[56:59], v182, s[98:99]
	v_lshl_add_u32 v183, v181, 7, v184
	global_load_dwordx4 v[60:63], v183, s[98:99]
	global_load_dwordx2 v[208:209], v[74:75], off
	global_load_dwordx2 v[208:209], v[74:75], off
	global_load_dwordx2 v[202:203], v[192:193], off nt
	global_load_dwordx2 v[204:205], v[200:201], off
	s_add_i32 s101, s101, 1
	s_cmp_lt_u32 s101, s33
	s_cbranch_scc1 .Lvp_nw_p
	s_mov_b32 s101, 0
	s_add_i32 s0, s0, 1
	s_cmp_lt_u32 s0, 16
	s_cbranch_scc0 .Lvp_rst_p
	s_add_u32 s98, s98, 0x200000
	s_addc_u32 s99, s99, 0
	v_lshl_add_u64 v[196:197], v[196:197], 0, s[30:31]
	v_lshl_add_u64 v[198:199], v[198:199], 0, s[78:79]
	v_lshl_add_u64 v[200:201], v[200:201], 0, s[30:31]
	s_branch .Lvp_wj_p
.Lvp_rst_p:
	s_mov_b32 s0, 0
	s_add_u32 s98, s50, 0x6000000
	s_addc_u32 s99, s51, 0
	v_mov_b64_e32 v[196:197], v[90:91]
	v_mov_b64_e32 v[198:199], v[88:89]
	v_mov_b64_e32 v[200:201], v[74:75]
.Lvp_wj_p:
	v_mov_b64_e32 v[192:193], v[196:197]
	v_mov_b64_e32 v[194:195], v[198:199]
	v_mov_b32_e32 v185, v124
	s_branch .Lvp_jn_p
.Lvp_nw_p:
	v_lshl_add_u64 v[192:193], v[192:193], 0, s[74:75]
	v_lshl_add_u64 v[194:195], v[194:195], 0, s[68:69]
	v_add_u32_e32 v185, 0x200, v185
.Lvp_jn_p:
	ds_read2_b32 v[166:167], v185 offset1:8
	ds_read2_b32 v[168:169], v185 offset0:16 offset1:24
	ds_read2_b32 v[170:171], v185 offset0:32 offset1:40
	ds_read2_b32 v[172:173], v185 offset0:48 offset1:56
	ds_read2_b32 v[174:175], v185 offset0:64 offset1:72
	ds_read2_b32 v[176:177], v185 offset0:80 offset1:88
	ds_read2_b32 v[178:179], v185 offset0:96 offset1:104
	ds_read2_b32 v[180:181], v185 offset0:112 offset1:120
; __global__ void __launch_bounds__(NTHR, 2) fwd_megakernel(Args a) {
;     ...
;                     for (int i = 0; i < 16; ++i) { const unsigned e = (unsigned)EL[k * 128 + 8 * i + grp]; r[i] = *(const u32x4*)(Vs + e * 128u); wi[i] = HW[k * 128 + 8 * i + grp]; }
;                     float* hp = H + t * D + vs * 128 + 2 * sp;
;                     f32x2 hv = __builtin_nontemporal_load((const f32x2*)hp);
;                     const f32x2 gn = *(const f32x2*)(a.ple_norm + vs * 128 + 2 * sp);
;                     f32x2 o2[8];
; #pragma unroll
;                     for (int q = 0; q < 8; ++q) o2[q] = (f32x2){0.f, 0.f};
; #pragma unroll
;                     for (int i = 0; i < 16; ++i) { const f32x2 ww = {wi[i], wi[i]};
; #pragma unroll
;                         for (int q = 0; q < 4; ++q) { const int w = (int)r[i][q]; o2[2 * q] += ww * __builtin_amdgcn_cvt_pk_f32_fp8(w, false); o2[2 * q + 1] += ww * __builtin_amdgcn_cvt_pk_f32_fp8(w, true); } }
.Lvp_loop:
	v_cmp_eq_u32_e32 vcc, s1, v125
	s_waitcnt vmcnt(19)
	v_cvt_pk_f32_fp8_e32 v[116:117], v0
	v_cvt_pk_f32_fp8_sdwa v[118:119], v0 src0_sel:WORD_1
	s_waitcnt lgkmcnt(0)
	v_pk_fma_f32 v[98:99], v[150:151], v[116:117], 0 op_sel_hi:[0,1,0]
	v_cvt_pk_f32_fp8_e32 v[120:121], v1
	v_pk_fma_f32 v[100:101], v[150:151], v[118:119], 0 op_sel_hi:[0,1,0]
	v_cvt_pk_f32_fp8_sdwa v[122:123], v1 src0_sel:WORD_1
	v_pk_fma_f32 v[102:103], v[150:151], v[120:121], 0 op_sel_hi:[0,1,0]
	v_cvt_pk_f32_fp8_e32 v[116:117], v2
	v_pk_fma_f32 v[104:105], v[150:151], v[122:123], 0 op_sel_hi:[0,1,0]
	v_cvt_pk_f32_fp8_sdwa v[118:119], v2 src0_sel:WORD_1
	v_pk_fma_f32 v[106:107], v[150:151], v[116:117], 0 op_sel_hi:[0,1,0]
	v_cvt_pk_f32_fp8_e32 v[120:121], v3
	v_pk_fma_f32 v[108:109], v[150:151], v[118:119], 0 op_sel_hi:[0,1,0]
	v_cvt_pk_f32_fp8_sdwa v[122:123], v3 src0_sel:WORD_1
	v_lshl_add_u32 v182, v166, 7, v184
	v_pk_fma_f32 v[110:111], v[150:151], v[120:121], 0 op_sel_hi:[0,1,0]
	global_load_dwordx4 v[0:3], v182, s[98:99]
	v_pk_fma_f32 v[112:113], v[150:151], v[122:123], 0 op_sel_hi:[0,1,0]
	s_waitcnt vmcnt(19)
	v_cvt_pk_f32_fp8_e32 v[116:117], v4
	v_cvt_pk_f32_fp8_sdwa v[118:119], v4 src0_sel:WORD_1
	v_pk_fma_f32 v[98:99], v[150:151], v[116:117], v[98:99] op_sel:[1,0,0] op_sel_hi:[1,1,1]
	v_cvt_pk_f32_fp8_e32 v[120:121], v5
	v_pk_fma_f32 v[100:101], v[150:151], v[118:119], v[100:101] op_sel:[1,0,0] op_sel_hi:[1,1,1]
	v_cvt_pk_f32_fp8_sdwa v[122:123], v5 src0_sel:WORD_1
	v_pk_fma_f32 v[102:103], v[150:151], v[120:121], v[102:103] op_sel:[1,0,0] op_sel_hi:[1,1,1]
	v_cvt_pk_f32_fp8_e32 v[116:117], v6
	v_pk_fma_f32 v[104:105], v[150:151], v[122:123], v[104:105] op_sel:[1,0,0] op_sel_hi:[1,1,1]
	v_cvt_pk_f32_fp8_sdwa v[118:119], v6 src0_sel:WORD_1
	v_pk_fma_f32 v[106:107], v[150:151], v[116:117], v[106:107] op_sel:[1,0,0] op_sel_hi:[1,1,1]
	v_cvt_pk_f32_fp8_e32 v[120:121], v7
	v_pk_fma_f32 v[108:109], v[150:151], v[118:119], v[108:109] op_sel:[1,0,0] op_sel_hi:[1,1,1]
	v_cvt_pk_f32_fp8_sdwa v[122:123], v7 src0_sel:WORD_1
	v_lshl_add_u32 v183, v167, 7, v184
	v_pk_fma_f32 v[110:111], v[150:151], v[120:121], v[110:111] op_sel:[1,0,0] op_sel_hi:[1,1,1]
	global_load_dwordx4 v[4:7], v183, s[98:99]
	v_pk_fma_f32 v[112:113], v[150:151], v[122:123], v[112:113] op_sel:[1,0,0] op_sel_hi:[1,1,1]
	s_waitcnt vmcnt(19)
	v_cvt_pk_f32_fp8_e32 v[116:117], v8
	v_cvt_pk_f32_fp8_sdwa v[118:119], v8 src0_sel:WORD_1
	v_pk_fma_f32 v[98:99], v[152:153], v[116:117], v[98:99] op_sel_hi:[0,1,1]
	v_cvt_pk_f32_fp8_e32 v[120:121], v9
	v_pk_fma_f32 v[100:101], v[152:153], v[118:119], v[100:101] op_sel_hi:[0,1,1]
	v_cvt_pk_f32_fp8_sdwa v[122:123], v9 src0_sel:WORD_1
	v_pk_fma_f32 v[102:103], v[152:153], v[120:121], v[102:103] op_sel_hi:[0,1,1]
	v_cvt_pk_f32_fp8_e32 v[116:117], v10
	v_pk_fma_f32 v[104:105], v[152:153], v[122:123], v[104:105] op_sel_hi:[0,1,1]
	v_cvt_pk_f32_fp8_sdwa v[118:119], v10 src0_sel:WORD_1
	v_pk_fma_f32 v[106:107], v[152:153], v[116:117], v[106:107] op_sel_hi:[0,1,1]
	v_cvt_pk_f32_fp8_e32 v[120:121], v11
	v_pk_fma_f32 v[108:109], v[152:153], v[118:119], v[108:109] op_sel_hi:[0,1,1]
	v_cvt_pk_f32_fp8_sdwa v[122:123], v11 src0_sel:WORD_1
	v_lshl_add_u32 v182, v168, 7, v184
	v_pk_fma_f32 v[110:111], v[152:153], v[120:121], v[110:111] op_sel_hi:[0,1,1]
	global_load_dwordx4 v[8:11], v182, s[98:99]
	v_pk_fma_f32 v[112:113], v[152:153], v[122:123], v[112:113] op_sel_hi:[0,1,1]
	s_waitcnt vmcnt(19)
	v_cvt_pk_f32_fp8_e32 v[116:117], v12
	v_cvt_pk_f32_fp8_sdwa v[118:119], v12 src0_sel:WORD_1
	v_pk_fma_f32 v[98:99], v[152:153], v[116:117], v[98:99] op_sel:[1,0,0] op_sel_hi:[1,1,1]
	v_cvt_pk_f32_fp8_e32 v[120:121], v13
	v_pk_fma_f32 v[100:101], v[152:153], v[118:119], v[100:101] op_sel:[1,0,0] op_sel_hi:[1,1,1]
	v_cvt_pk_f32_fp8_sdwa v[122:123], v13 src0_sel:WORD_1
	v_pk_fma_f32 v[102:103], v[152:153], v[120:121], v[102:103] op_sel:[1,0,0] op_sel_hi:[1,1,1]
	v_cvt_pk_f32_fp8_e32 v[116:117], v14
	v_pk_fma_f32 v[104:105], v[152:153], v[122:123], v[104:105] op_sel:[1,0,0] op_sel_hi:[1,1,1]
	v_cvt_pk_f32_fp8_sdwa v[118:119], v14 src0_sel:WORD_1
	v_pk_fma_f32 v[106:107], v[152:153], v[116:117], v[106:107] op_sel:[1,0,0] op_sel_hi:[1,1,1]
	v_cvt_pk_f32_fp8_e32 v[120:121], v15
	v_pk_fma_f32 v[108:109], v[152:153], v[118:119], v[108:109] op_sel:[1,0,0] op_sel_hi:[1,1,1]
	v_cvt_pk_f32_fp8_sdwa v[122:123], v15 src0_sel:WORD_1
	v_lshl_add_u32 v183, v169, 7, v184
	v_pk_fma_f32 v[110:111], v[152:153], v[120:121], v[110:111] op_sel:[1,0,0] op_sel_hi:[1,1,1]
	global_load_dwordx4 v[12:15], v183, s[98:99]
	v_pk_fma_f32 v[112:113], v[152:153], v[122:123], v[112:113] op_sel:[1,0,0] op_sel_hi:[1,1,1]
	s_waitcnt vmcnt(19)
	v_cvt_pk_f32_fp8_e32 v[116:117], v16
	v_cvt_pk_f32_fp8_sdwa v[118:119], v16 src0_sel:WORD_1
	v_pk_fma_f32 v[98:99], v[154:155], v[116:117], v[98:99] op_sel_hi:[0,1,1]
	v_cvt_pk_f32_fp8_e32 v[120:121], v17
	v_pk_fma_f32 v[100:101], v[154:155], v[118:119], v[100:101] op_sel_hi:[0,1,1]
	v_cvt_pk_f32_fp8_sdwa v[122:123], v17 src0_sel:WORD_1
	v_pk_fma_f32 v[102:103], v[154:155], v[120:121], v[102:103] op_sel_hi:[0,1,1]
	v_cvt_pk_f32_fp8_e32 v[116:117], v18
	v_pk_fma_f32 v[104:105], v[154:155], v[122:123], v[104:105] op_sel_hi:[0,1,1]
	v_cvt_pk_f32_fp8_sdwa v[118:119], v18 src0_sel:WORD_1
	v_pk_fma_f32 v[106:107], v[154:155], v[116:117], v[106:107] op_sel_hi:[0,1,1]
	v_cvt_pk_f32_fp8_e32 v[120:121], v19
	v_pk_fma_f32 v[108:109], v[154:155], v[118:119], v[108:109] op_sel_hi:[0,1,1]
	v_cvt_pk_f32_fp8_sdwa v[122:123], v19 src0_sel:WORD_1
	v_lshl_add_u32 v182, v170, 7, v184
	v_pk_fma_f32 v[110:111], v[154:155], v[120:121], v[110:111] op_sel_hi:[0,1,1]
	global_load_dwordx4 v[16:19], v182, s[98:99]
	v_pk_fma_f32 v[112:113], v[154:155], v[122:123], v[112:113] op_sel_hi:[0,1,1]
	s_waitcnt vmcnt(19)
; __global__ void __launch_bounds__(NTHR, 2) fwd_megakernel(Args a) {
;     ...
; #pragma unroll
;                     for (int i = 0; i < 16; ++i) { const f32x2 ww = {wi[i], wi[i]};
; #pragma unroll
;                         for (int q = 0; q < 4; ++q) { const int w = (int)r[i][q]; o2[2 * q] += ww * __builtin_amdgcn_cvt_pk_f32_fp8(w, false); o2[2 * q + 1] += ww * __builtin_amdgcn_cvt_pk_f32_fp8(w, true); } }
	v_cvt_pk_f32_fp8_e32 v[116:117], v20
	v_cvt_pk_f32_fp8_sdwa v[118:119], v20 src0_sel:WORD_1
	v_pk_fma_f32 v[98:99], v[154:155], v[116:117], v[98:99] op_sel:[1,0,0] op_sel_hi:[1,1,1]
	v_cvt_pk_f32_fp8_e32 v[120:121], v21
	v_pk_fma_f32 v[100:101], v[154:155], v[118:119], v[100:101] op_sel:[1,0,0] op_sel_hi:[1,1,1]
	v_cvt_pk_f32_fp8_sdwa v[122:123], v21 src0_sel:WORD_1
	v_pk_fma_f32 v[102:103], v[154:155], v[120:121], v[102:103] op_sel:[1,0,0] op_sel_hi:[1,1,1]
	v_cvt_pk_f32_fp8_e32 v[116:117], v22
	v_pk_fma_f32 v[104:105], v[154:155], v[122:123], v[104:105] op_sel:[1,0,0] op_sel_hi:[1,1,1]
	v_cvt_pk_f32_fp8_sdwa v[118:119], v22 src0_sel:WORD_1
	v_pk_fma_f32 v[106:107], v[154:155], v[116:117], v[106:107] op_sel:[1,0,0] op_sel_hi:[1,1,1]
	v_cvt_pk_f32_fp8_e32 v[120:121], v23
	v_pk_fma_f32 v[108:109], v[154:155], v[118:119], v[108:109] op_sel:[1,0,0] op_sel_hi:[1,1,1]
	v_cvt_pk_f32_fp8_sdwa v[122:123], v23 src0_sel:WORD_1
	v_lshl_add_u32 v183, v171, 7, v184
	v_pk_fma_f32 v[110:111], v[154:155], v[120:121], v[110:111] op_sel:[1,0,0] op_sel_hi:[1,1,1]
	global_load_dwordx4 v[20:23], v183, s[98:99]
	v_pk_fma_f32 v[112:113], v[154:155], v[122:123], v[112:113] op_sel:[1,0,0] op_sel_hi:[1,1,1]
	s_waitcnt vmcnt(19)
	v_cvt_pk_f32_fp8_e32 v[116:117], v24
	v_cvt_pk_f32_fp8_sdwa v[118:119], v24 src0_sel:WORD_1
	v_pk_fma_f32 v[98:99], v[156:157], v[116:117], v[98:99] op_sel_hi:[0,1,1]
	v_cvt_pk_f32_fp8_e32 v[120:121], v25
	v_pk_fma_f32 v[100:101], v[156:157], v[118:119], v[100:101] op_sel_hi:[0,1,1]
	v_cvt_pk_f32_fp8_sdwa v[122:123], v25 src0_sel:WORD_1
	v_pk_fma_f32 v[102:103], v[156:157], v[120:121], v[102:103] op_sel_hi:[0,1,1]
	v_cvt_pk_f32_fp8_e32 v[116:117], v26
	v_pk_fma_f32 v[104:105], v[156:157], v[122:123], v[104:105] op_sel_hi:[0,1,1]
	v_cvt_pk_f32_fp8_sdwa v[118:119], v26 src0_sel:WORD_1
	v_pk_fma_f32 v[106:107], v[156:157], v[116:117], v[106:107] op_sel_hi:[0,1,1]
	v_cvt_pk_f32_fp8_e32 v[120:121], v27
	v_pk_fma_f32 v[108:109], v[156:157], v[118:119], v[108:109] op_sel_hi:[0,1,1]
	v_cvt_pk_f32_fp8_sdwa v[122:123], v27 src0_sel:WORD_1
	v_lshl_add_u32 v182, v172, 7, v184
	v_pk_fma_f32 v[110:111], v[156:157], v[120:121], v[110:111] op_sel_hi:[0,1,1]
	global_load_dwordx4 v[24:27], v182, s[98:99]
	v_pk_fma_f32 v[112:113], v[156:157], v[122:123], v[112:113] op_sel_hi:[0,1,1]
	s_waitcnt vmcnt(19)
	v_cvt_pk_f32_fp8_e32 v[116:117], v28
	v_cvt_pk_f32_fp8_sdwa v[118:119], v28 src0_sel:WORD_1
	v_pk_fma_f32 v[98:99], v[156:157], v[116:117], v[98:99] op_sel:[1,0,0] op_sel_hi:[1,1,1]
	v_cvt_pk_f32_fp8_e32 v[120:121], v29
	v_pk_fma_f32 v[100:101], v[156:157], v[118:119], v[100:101] op_sel:[1,0,0] op_sel_hi:[1,1,1]
	v_cvt_pk_f32_fp8_sdwa v[122:123], v29 src0_sel:WORD_1
	v_pk_fma_f32 v[102:103], v[156:157], v[120:121], v[102:103] op_sel:[1,0,0] op_sel_hi:[1,1,1]
	v_cvt_pk_f32_fp8_e32 v[116:117], v30
	v_pk_fma_f32 v[104:105], v[156:157], v[122:123], v[104:105] op_sel:[1,0,0] op_sel_hi:[1,1,1]
	v_cvt_pk_f32_fp8_sdwa v[118:119], v30 src0_sel:WORD_1
	v_pk_fma_f32 v[106:107], v[156:157], v[116:117], v[106:107] op_sel:[1,0,0] op_sel_hi:[1,1,1]
	v_cvt_pk_f32_fp8_e32 v[120:121], v31
	v_pk_fma_f32 v[108:109], v[156:157], v[118:119], v[108:109] op_sel:[1,0,0] op_sel_hi:[1,1,1]
	v_cvt_pk_f32_fp8_sdwa v[122:123], v31 src0_sel:WORD_1
	v_lshl_add_u32 v183, v173, 7, v184
	v_pk_fma_f32 v[110:111], v[156:157], v[120:121], v[110:111] op_sel:[1,0,0] op_sel_hi:[1,1,1]
	global_load_dwordx4 v[28:31], v183, s[98:99]
	v_pk_fma_f32 v[112:113], v[156:157], v[122:123], v[112:113] op_sel:[1,0,0] op_sel_hi:[1,1,1]
	s_waitcnt vmcnt(19)
	v_cvt_pk_f32_fp8_e32 v[116:117], v32
	v_cvt_pk_f32_fp8_sdwa v[118:119], v32 src0_sel:WORD_1
	v_pk_fma_f32 v[98:99], v[158:159], v[116:117], v[98:99] op_sel_hi:[0,1,1]
	v_cvt_pk_f32_fp8_e32 v[120:121], v33
	v_pk_fma_f32 v[100:101], v[158:159], v[118:119], v[100:101] op_sel_hi:[0,1,1]
	v_cvt_pk_f32_fp8_sdwa v[122:123], v33 src0_sel:WORD_1
	v_pk_fma_f32 v[102:103], v[158:159], v[120:121], v[102:103] op_sel_hi:[0,1,1]
	v_cvt_pk_f32_fp8_e32 v[116:117], v34
	v_pk_fma_f32 v[104:105], v[158:159], v[122:123], v[104:105] op_sel_hi:[0,1,1]
	v_cvt_pk_f32_fp8_sdwa v[118:119], v34 src0_sel:WORD_1
	v_pk_fma_f32 v[106:107], v[158:159], v[116:117], v[106:107] op_sel_hi:[0,1,1]
	v_cvt_pk_f32_fp8_e32 v[120:121], v35
	v_pk_fma_f32 v[108:109], v[158:159], v[118:119], v[108:109] op_sel_hi:[0,1,1]
	v_cvt_pk_f32_fp8_sdwa v[122:123], v35 src0_sel:WORD_1
	v_lshl_add_u32 v182, v174, 7, v184
	v_pk_fma_f32 v[110:111], v[158:159], v[120:121], v[110:111] op_sel_hi:[0,1,1]
	global_load_dwordx4 v[32:35], v182, s[98:99]
	v_pk_fma_f32 v[112:113], v[158:159], v[122:123], v[112:113] op_sel_hi:[0,1,1]
	s_waitcnt vmcnt(19)
	v_cvt_pk_f32_fp8_e32 v[116:117], v36
	v_cvt_pk_f32_fp8_sdwa v[118:119], v36 src0_sel:WORD_1
	v_pk_fma_f32 v[98:99], v[158:159], v[116:117], v[98:99] op_sel:[1,0,0] op_sel_hi:[1,1,1]
	v_cvt_pk_f32_fp8_e32 v[120:121], v37
	v_pk_fma_f32 v[100:101], v[158:159], v[118:119], v[100:101] op_sel:[1,0,0] op_sel_hi:[1,1,1]
	v_cvt_pk_f32_fp8_sdwa v[122:123], v37 src0_sel:WORD_1
	v_pk_fma_f32 v[102:103], v[158:159], v[120:121], v[102:103] op_sel:[1,0,0] op_sel_hi:[1,1,1]
	v_cvt_pk_f32_fp8_e32 v[116:117], v38
	v_pk_fma_f32 v[104:105], v[158:159], v[122:123], v[104:105] op_sel:[1,0,0] op_sel_hi:[1,1,1]
	v_cvt_pk_f32_fp8_sdwa v[118:119], v38 src0_sel:WORD_1
	v_pk_fma_f32 v[106:107], v[158:159], v[116:117], v[106:107] op_sel:[1,0,0] op_sel_hi:[1,1,1]
	v_cvt_pk_f32_fp8_e32 v[120:121], v39
	v_pk_fma_f32 v[108:109], v[158:159], v[118:119], v[108:109] op_sel:[1,0,0] op_sel_hi:[1,1,1]
	v_cvt_pk_f32_fp8_sdwa v[122:123], v39 src0_sel:WORD_1
	v_lshl_add_u32 v183, v175, 7, v184
	v_pk_fma_f32 v[110:111], v[158:159], v[120:121], v[110:111] op_sel:[1,0,0] op_sel_hi:[1,1,1]
	global_load_dwordx4 v[36:39], v183, s[98:99]
	v_pk_fma_f32 v[112:113], v[158:159], v[122:123], v[112:113] op_sel:[1,0,0] op_sel_hi:[1,1,1]
	s_waitcnt vmcnt(19)
; __global__ void __launch_bounds__(NTHR, 2) fwd_megakernel(Args a) {
;     ...
; #pragma unroll
;                     for (int i = 0; i < 16; ++i) { const f32x2 ww = {wi[i], wi[i]};
; #pragma unroll
;                         for (int q = 0; q < 4; ++q) { const int w = (int)r[i][q]; o2[2 * q] += ww * __builtin_amdgcn_cvt_pk_f32_fp8(w, false); o2[2 * q + 1] += ww * __builtin_amdgcn_cvt_pk_f32_fp8(w, true); } }
	v_cvt_pk_f32_fp8_e32 v[116:117], v40
	v_cvt_pk_f32_fp8_sdwa v[118:119], v40 src0_sel:WORD_1
	v_pk_fma_f32 v[98:99], v[160:161], v[116:117], v[98:99] op_sel_hi:[0,1,1]
	v_cvt_pk_f32_fp8_e32 v[120:121], v41
	v_pk_fma_f32 v[100:101], v[160:161], v[118:119], v[100:101] op_sel_hi:[0,1,1]
	v_cvt_pk_f32_fp8_sdwa v[122:123], v41 src0_sel:WORD_1
	v_pk_fma_f32 v[102:103], v[160:161], v[120:121], v[102:103] op_sel_hi:[0,1,1]
	v_cvt_pk_f32_fp8_e32 v[116:117], v42
	v_pk_fma_f32 v[104:105], v[160:161], v[122:123], v[104:105] op_sel_hi:[0,1,1]
	v_cvt_pk_f32_fp8_sdwa v[118:119], v42 src0_sel:WORD_1
	v_pk_fma_f32 v[106:107], v[160:161], v[116:117], v[106:107] op_sel_hi:[0,1,1]
	v_cvt_pk_f32_fp8_e32 v[120:121], v43
	v_pk_fma_f32 v[108:109], v[160:161], v[118:119], v[108:109] op_sel_hi:[0,1,1]
	v_cvt_pk_f32_fp8_sdwa v[122:123], v43 src0_sel:WORD_1
	v_lshl_add_u32 v182, v176, 7, v184
	v_pk_fma_f32 v[110:111], v[160:161], v[120:121], v[110:111] op_sel_hi:[0,1,1]
	global_load_dwordx4 v[40:43], v182, s[98:99]
	v_pk_fma_f32 v[112:113], v[160:161], v[122:123], v[112:113] op_sel_hi:[0,1,1]
	s_waitcnt vmcnt(19)
	v_cvt_pk_f32_fp8_e32 v[116:117], v44
	v_cvt_pk_f32_fp8_sdwa v[118:119], v44 src0_sel:WORD_1
	v_pk_fma_f32 v[98:99], v[160:161], v[116:117], v[98:99] op_sel:[1,0,0] op_sel_hi:[1,1,1]
	v_cvt_pk_f32_fp8_e32 v[120:121], v45
	v_pk_fma_f32 v[100:101], v[160:161], v[118:119], v[100:101] op_sel:[1,0,0] op_sel_hi:[1,1,1]
	v_cvt_pk_f32_fp8_sdwa v[122:123], v45 src0_sel:WORD_1
	v_pk_fma_f32 v[102:103], v[160:161], v[120:121], v[102:103] op_sel:[1,0,0] op_sel_hi:[1,1,1]
	v_cvt_pk_f32_fp8_e32 v[116:117], v46
	v_pk_fma_f32 v[104:105], v[160:161], v[122:123], v[104:105] op_sel:[1,0,0] op_sel_hi:[1,1,1]
	v_cvt_pk_f32_fp8_sdwa v[118:119], v46 src0_sel:WORD_1
	v_pk_fma_f32 v[106:107], v[160:161], v[116:117], v[106:107] op_sel:[1,0,0] op_sel_hi:[1,1,1]
	v_cvt_pk_f32_fp8_e32 v[120:121], v47
	v_pk_fma_f32 v[108:109], v[160:161], v[118:119], v[108:109] op_sel:[1,0,0] op_sel_hi:[1,1,1]
	v_cvt_pk_f32_fp8_sdwa v[122:123], v47 src0_sel:WORD_1
	v_lshl_add_u32 v183, v177, 7, v184
	v_pk_fma_f32 v[110:111], v[160:161], v[120:121], v[110:111] op_sel:[1,0,0] op_sel_hi:[1,1,1]
	global_load_dwordx4 v[44:47], v183, s[98:99]
	v_pk_fma_f32 v[112:113], v[160:161], v[122:123], v[112:113] op_sel:[1,0,0] op_sel_hi:[1,1,1]
	s_waitcnt vmcnt(19)
	v_cvt_pk_f32_fp8_e32 v[116:117], v48
	v_cvt_pk_f32_fp8_sdwa v[118:119], v48 src0_sel:WORD_1
	v_pk_fma_f32 v[98:99], v[162:163], v[116:117], v[98:99] op_sel_hi:[0,1,1]
	v_cvt_pk_f32_fp8_e32 v[120:121], v49
	v_pk_fma_f32 v[100:101], v[162:163], v[118:119], v[100:101] op_sel_hi:[0,1,1]
	v_cvt_pk_f32_fp8_sdwa v[122:123], v49 src0_sel:WORD_1
	v_pk_fma_f32 v[102:103], v[162:163], v[120:121], v[102:103] op_sel_hi:[0,1,1]
	v_cvt_pk_f32_fp8_e32 v[116:117], v50
	v_pk_fma_f32 v[104:105], v[162:163], v[122:123], v[104:105] op_sel_hi:[0,1,1]
	v_cvt_pk_f32_fp8_sdwa v[118:119], v50 src0_sel:WORD_1
	v_pk_fma_f32 v[106:107], v[162:163], v[116:117], v[106:107] op_sel_hi:[0,1,1]
	v_cvt_pk_f32_fp8_e32 v[120:121], v51
	v_pk_fma_f32 v[108:109], v[162:163], v[118:119], v[108:109] op_sel_hi:[0,1,1]
	v_cvt_pk_f32_fp8_sdwa v[122:123], v51 src0_sel:WORD_1
	v_lshl_add_u32 v182, v178, 7, v184
	v_pk_fma_f32 v[110:111], v[162:163], v[120:121], v[110:111] op_sel_hi:[0,1,1]
	global_load_dwordx4 v[48:51], v182, s[98:99]
	v_pk_fma_f32 v[112:113], v[162:163], v[122:123], v[112:113] op_sel_hi:[0,1,1]
	s_waitcnt vmcnt(19)
; __global__ void __launch_bounds__(NTHR, 2) fwd_megakernel(Args a) {
;     ...
;             for (int vs = 0; vs < 16; ++vs) {
;                 const unsigned char* Vs = V8 + (size_t)vs * (16384 * 128) + sub * 16;
; #pragma unroll 1
;                 for (int k = 0; k < kn; ++k) {
;                     const size_t t = (size_t)gw + (size_t)(k0 + k) * NGW;
;     ...
; #pragma unroll
;                     for (int i = 0; i < 16; ++i) { const f32x2 ww = {wi[i], wi[i]};
; #pragma unroll
;                         for (int q = 0; q < 4; ++q) { const int w = (int)r[i][q]; o2[2 * q] += ww * __builtin_amdgcn_cvt_pk_f32_fp8(w, false); o2[2 * q + 1] += ww * __builtin_amdgcn_cvt_pk_f32_fp8(w, true); } }
	v_cvt_pk_f32_fp8_e32 v[116:117], v52
	v_cvt_pk_f32_fp8_sdwa v[118:119], v52 src0_sel:WORD_1
	v_pk_fma_f32 v[98:99], v[162:163], v[116:117], v[98:99] op_sel:[1,0,0] op_sel_hi:[1,1,1]
	v_cvt_pk_f32_fp8_e32 v[120:121], v53
	v_pk_fma_f32 v[100:101], v[162:163], v[118:119], v[100:101] op_sel:[1,0,0] op_sel_hi:[1,1,1]
	v_cvt_pk_f32_fp8_sdwa v[122:123], v53 src0_sel:WORD_1
	v_pk_fma_f32 v[102:103], v[162:163], v[120:121], v[102:103] op_sel:[1,0,0] op_sel_hi:[1,1,1]
	v_cvt_pk_f32_fp8_e32 v[116:117], v54
	v_pk_fma_f32 v[104:105], v[162:163], v[122:123], v[104:105] op_sel:[1,0,0] op_sel_hi:[1,1,1]
	v_cvt_pk_f32_fp8_sdwa v[118:119], v54 src0_sel:WORD_1
	v_pk_fma_f32 v[106:107], v[162:163], v[116:117], v[106:107] op_sel:[1,0,0] op_sel_hi:[1,1,1]
	v_cvt_pk_f32_fp8_e32 v[120:121], v55
	v_pk_fma_f32 v[108:109], v[162:163], v[118:119], v[108:109] op_sel:[1,0,0] op_sel_hi:[1,1,1]
	v_cvt_pk_f32_fp8_sdwa v[122:123], v55 src0_sel:WORD_1
	v_lshl_add_u32 v183, v179, 7, v184
	v_pk_fma_f32 v[110:111], v[162:163], v[120:121], v[110:111] op_sel:[1,0,0] op_sel_hi:[1,1,1]
	global_load_dwordx4 v[52:55], v183, s[98:99]
	v_pk_fma_f32 v[112:113], v[162:163], v[122:123], v[112:113] op_sel:[1,0,0] op_sel_hi:[1,1,1]
	s_waitcnt vmcnt(19)
	v_cvt_pk_f32_fp8_e32 v[116:117], v56
	v_cvt_pk_f32_fp8_sdwa v[118:119], v56 src0_sel:WORD_1
	v_pk_fma_f32 v[98:99], v[164:165], v[116:117], v[98:99] op_sel_hi:[0,1,1]
	v_cvt_pk_f32_fp8_e32 v[120:121], v57
	v_pk_fma_f32 v[100:101], v[164:165], v[118:119], v[100:101] op_sel_hi:[0,1,1]
	v_cvt_pk_f32_fp8_sdwa v[122:123], v57 src0_sel:WORD_1
	v_pk_fma_f32 v[102:103], v[164:165], v[120:121], v[102:103] op_sel_hi:[0,1,1]
	v_cvt_pk_f32_fp8_e32 v[116:117], v58
	v_pk_fma_f32 v[104:105], v[164:165], v[122:123], v[104:105] op_sel_hi:[0,1,1]
	v_cvt_pk_f32_fp8_sdwa v[118:119], v58 src0_sel:WORD_1
	v_pk_fma_f32 v[106:107], v[164:165], v[116:117], v[106:107] op_sel_hi:[0,1,1]
	v_cvt_pk_f32_fp8_e32 v[120:121], v59
	v_pk_fma_f32 v[108:109], v[164:165], v[118:119], v[108:109] op_sel_hi:[0,1,1]
	v_cvt_pk_f32_fp8_sdwa v[122:123], v59 src0_sel:WORD_1
	v_lshl_add_u32 v182, v180, 7, v184
	v_pk_fma_f32 v[110:111], v[164:165], v[120:121], v[110:111] op_sel_hi:[0,1,1]
	global_load_dwordx4 v[56:59], v182, s[98:99]
	v_pk_fma_f32 v[112:113], v[164:165], v[122:123], v[112:113] op_sel_hi:[0,1,1]
	s_waitcnt vmcnt(19)
	v_cvt_pk_f32_fp8_e32 v[116:117], v60
	v_cvt_pk_f32_fp8_sdwa v[118:119], v60 src0_sel:WORD_1
	v_pk_fma_f32 v[98:99], v[164:165], v[116:117], v[98:99] op_sel:[1,0,0] op_sel_hi:[1,1,1]
	v_cvt_pk_f32_fp8_e32 v[120:121], v61
	v_pk_fma_f32 v[100:101], v[164:165], v[118:119], v[100:101] op_sel:[1,0,0] op_sel_hi:[1,1,1]
	v_cvt_pk_f32_fp8_sdwa v[122:123], v61 src0_sel:WORD_1
	v_pk_fma_f32 v[102:103], v[164:165], v[120:121], v[102:103] op_sel:[1,0,0] op_sel_hi:[1,1,1]
	v_cvt_pk_f32_fp8_e32 v[116:117], v62
	v_pk_fma_f32 v[104:105], v[164:165], v[122:123], v[104:105] op_sel:[1,0,0] op_sel_hi:[1,1,1]
	v_cvt_pk_f32_fp8_sdwa v[118:119], v62 src0_sel:WORD_1
	v_pk_fma_f32 v[106:107], v[164:165], v[116:117], v[106:107] op_sel:[1,0,0] op_sel_hi:[1,1,1]
	v_cvt_pk_f32_fp8_e32 v[120:121], v63
	v_pk_fma_f32 v[108:109], v[164:165], v[118:119], v[108:109] op_sel:[1,0,0] op_sel_hi:[1,1,1]
	v_cvt_pk_f32_fp8_sdwa v[122:123], v63 src0_sel:WORD_1
	v_lshl_add_u32 v183, v181, 7, v184
	v_pk_fma_f32 v[110:111], v[164:165], v[120:121], v[110:111] op_sel:[1,0,0] op_sel_hi:[1,1,1]
	global_load_dwordx4 v[60:63], v183, s[98:99]
	v_pk_fma_f32 v[112:113], v[164:165], v[122:123], v[112:113] op_sel:[1,0,0] op_sel_hi:[1,1,1]
	v_add_u32_e32 v186, 0x2000, v185
	ds_read2_b32 v[150:151], v186 offset1:8
	ds_read2_b32 v[152:153], v186 offset0:16 offset1:24
	ds_read2_b32 v[154:155], v186 offset0:32 offset1:40
	ds_read2_b32 v[156:157], v186 offset0:48 offset1:56
	ds_read2_b32 v[158:159], v186 offset0:64 offset1:72
	ds_read2_b32 v[160:161], v186 offset0:80 offset1:88
	ds_read2_b32 v[162:163], v186 offset0:96 offset1:104
	ds_read2_b32 v[164:165], v186 offset0:112 offset1:120
	v_mov_b64_e32 v[210:211], v[192:193]
	v_mov_b64_e32 v[216:217], v[194:195]
	v_mov_b64_e32 v[212:213], v[200:201]
	s_mov_b32 s1, s101
	s_add_i32 s101, s101, 1
	s_cmp_lt_u32 s101, s33
	s_cbranch_scc1 .Lvp_nw_l
	s_mov_b32 s101, 0
	s_add_i32 s0, s0, 1
	s_cmp_lt_u32 s0, 16
	s_cbranch_scc0 .Lvp_rst_l
	s_add_u32 s98, s98, 0x200000
	s_addc_u32 s99, s99, 0
	v_lshl_add_u64 v[196:197], v[196:197], 0, s[30:31]
	v_lshl_add_u64 v[198:199], v[198:199], 0, s[78:79]
	v_lshl_add_u64 v[200:201], v[200:201], 0, s[30:31]
	s_branch .Lvp_wj_l

; __device__ __forceinline__ unsigned pk2(float lo, float hi) { f32x2 v = {lo, hi}; bf16x2_t b = __builtin_convertvector(v, bf16x2_t); return __builtin_bit_cast(unsigned, b); }
; #define DPP_ADD(v, ctrl) ((v) + __builtin_bit_cast(float, __builtin_amdgcn_update_dpp(0, __builtin_bit_cast(int, (v)), (ctrl), 0xf, 0xf, true)))
; __global__ void __launch_bounds__(NTHR, 2) fwd_megakernel(Args a) {
;     ...
;                     const bool b5 = lane & 32, b4 = lane & 16, b3 = lane & 8;
;                     f32x2 s4[4], s2[2], s1;
; #pragma unroll
;                     for (int q = 0; q < 4; ++q) { const f32x2 keep = b5 ? o2[q + 4] : o2[q], send = b5 ? o2[q] : o2[q + 4];
;                         s4[q] = keep + (f32x2){__shfl_xor(send.x, 32), __shfl_xor(send.y, 32)}; }
; #pragma unroll
;                     for (int q = 0; q < 2; ++q) { const f32x2 keep = b4 ? s4[q + 2] : s4[q], send = b4 ? s4[q] : s4[q + 2];
;                         s2[q] = keep + (f32x2){__shfl_xor(send.x, 16), __shfl_xor(send.y, 16)}; }
;                     { const f32x2 keep = b3 ? s2[1] : s2[0], send = b3 ? s2[0] : s2[1]; s1 = keep + (f32x2){__shfl_xor(send.x, 8), __shfl_xor(send.y, 8)}; }
;                     hv += s1;
;                     __builtin_nontemporal_store(hv, (f32x2*)hp);
;                     __builtin_nontemporal_store(pk2(hv.x * gn.x, hv.y * gn.y), (unsigned*)(Gb + t * D + vs * 128 + 2 * sp));
;                     float sq = hv.x * hv.x + hv.y * hv.y;
;                     sq = DPP_ADD(sq, 0xB1); sq = DPP_ADD(sq, 0x4E); sq = DPP_ADD(sq, 0x141); sq = DPP_ADD(sq, 0x140);
;                     ssk += ((lane & 15) == k) ? sq : 0.f;
;                 }
;             }
.Lvp_jn_l:
	ds_read2_b32 v[166:167], v185 offset1:8
	ds_read2_b32 v[168:169], v185 offset0:16 offset1:24
	ds_read2_b32 v[170:171], v185 offset0:32 offset1:40
	ds_read2_b32 v[172:173], v185 offset0:48 offset1:56
	ds_read2_b32 v[174:175], v185 offset0:64 offset1:72
	ds_read2_b32 v[176:177], v185 offset0:80 offset1:88
	ds_read2_b32 v[178:179], v185 offset0:96 offset1:104
	ds_read2_b32 v[180:181], v185 offset0:112 offset1:120
	v_permlane32_swap_b32_e32 v98, v106
	v_permlane32_swap_b32_e32 v99, v107
	v_permlane32_swap_b32_e32 v100, v108
	v_permlane32_swap_b32_e32 v101, v109
	v_permlane32_swap_b32_e32 v102, v110
	v_permlane32_swap_b32_e32 v103, v111
	v_permlane32_swap_b32_e32 v104, v112
	v_permlane32_swap_b32_e32 v105, v113
	v_pk_add_f32 v[98:99], v[98:99], v[106:107]
	v_pk_add_f32 v[100:101], v[100:101], v[108:109]
	v_pk_add_f32 v[102:103], v[102:103], v[110:111]
	v_pk_add_f32 v[104:105], v[104:105], v[112:113]
	s_nop 1
	v_permlane16_swap_b32_e32 v98, v102
	v_permlane16_swap_b32_e32 v99, v103
	v_permlane16_swap_b32_e32 v100, v104
	v_permlane16_swap_b32_e32 v101, v105
	v_pk_add_f32 v[98:99], v[98:99], v[102:103]
	v_pk_add_f32 v[100:101], v[100:101], v[104:105]
	s_nop 1
	v_add_f32_dpp v102, v98, v98 row_ror:8 row_mask:0xf bank_mask:0xf
	v_add_f32_dpp v103, v99, v99 row_ror:8 row_mask:0xf bank_mask:0xf
	v_add_f32_dpp v104, v100, v100 row_ror:8 row_mask:0xf bank_mask:0xf
	v_add_f32_dpp v105, v101, v101 row_ror:8 row_mask:0xf bank_mask:0xf
	v_cndmask_b32_e64 v106, v104, v102, s[10:11]
	v_cndmask_b32_e64 v107, v105, v103, s[10:11]
	s_waitcnt vmcnt(16)
	v_pk_add_f32 v[206:207], v[202:203], v[106:107]
	s_nop 0
	global_store_dwordx2 v[188:189], v[206:207], off nt
	v_pk_mul_f32 v[108:109], v[204:205], v[206:207]
	v_pk_mul_f32 v[110:111], v[206:207], v[206:207]
	s_nop 0
	v_cvt_pk_bf16_f32 v108, v108, v109
	v_add_f32_e32 v110, v110, v111
	global_store_dword v[190:191], v108, off nt
	global_load_dwordx2 v[202:203], v[210:211], off nt
	global_load_dwordx2 v[204:205], v[212:213], off
	v_add_f32_dpp v110, v110, v110 quad_perm:[1,0,3,2] row_mask:0xf bank_mask:0xf bound_ctrl:1
	v_mov_b64_e32 v[188:189], v[210:211]
	v_mov_b64_e32 v[190:191], v[216:217]
	v_add_f32_dpp v110, v110, v110 quad_perm:[2,3,0,1] row_mask:0xf bank_mask:0xf bound_ctrl:1
	s_add_i32 s100, s100, -1
	s_nop 0
	v_add_f32_dpp v110, v110, v110 row_half_mirror row_mask:0xf bank_mask:0xf bound_ctrl:1
	s_nop 1
	v_add_f32_dpp v110, v110, v110 row_mirror row_mask:0xf bank_mask:0xf bound_ctrl:1
	s_cmp_lg_u32 s100, 0
	v_cndmask_b32_e32 v111, 0, v110, vcc
	v_add_f32_e32 v134, v134, v111
	s_cbranch_scc1 .Lvp_loop
	s_waitcnt vmcnt(0)
	s_waitcnt lgkmcnt(0)
	s_branch .LBB0_917
